# v23 plus separate straight-line attention tile-loop copies for the two wave halves (barrier placement baked in, no per-tile group branch)
# speedup vs baseline: 1.0047x; 1.0047x over previous
; #define DMA(slot, t) do { \
;     __builtin_amdgcn_global_load_lds((const unsigned*)(Kg + (long)(t) * (64 * 256)), (LAS unsigned*)(L3 + K_OFF + (slot) * SHM_T + wid * 1024), 16, 0, 0); \
;     __builtin_amdgcn_global_load_lds((const unsigned*)(Vg + (long)(t) * 8192), (LAS unsigned*)(L3 + (slot) * SHM_T + wid * 1024), 16, 0, 0); } while (0)
; #define BAR() do { asm volatile("s_waitcnt lgkmcnt(0)" ::: "memory"); __builtin_amdgcn_s_barrier(); asm volatile("" ::: "memory"); } while (0)
; #define WAITV(n) asm volatile("s_waitcnt vmcnt(" #n ")" ::: "memory")
; #define QKT(P0, P1, b) qkt(P0, P1, nm, K_lds + (b) * SHM_T, qr, ko, c00, c01, c10, c11)
; __device__ __forceinline__ void partialSM_first(f32x16& p0, f32x16& p1, f32x16& nm) {
;   const float delta = max32(p0, p1) - PSHIFT;
;   for (int r = 0; r < 16; ++r) { p0[r] -= delta; p1[r] -= delta; nm[r] -= delta; }
;   for (int r = 0; r < 16; ++r) p0[r] = __builtin_amdgcn_exp2f(p0[r]);
; }
; __device__ __forceinline__ void body(const unsigned char* Q8b, const unsigned char* K8h, const unsigned char* VT8h, const bf16_t* Gb, bf16_t* Ob, int seq, char* lds, const int wid, ...
;     ...
;   if (!pre) { DMA(0, 0); DMA(1, 1); } else BAR();
;   DMA(2, 2);
;   WAITV(2); BAR();
;   QKT(pA0, pA1, 0); partialSM_first(pA0, pA1, nm);
.LBB0_371:
	s_mov_b32 m0, s76
	v_lshl_add_u64 v[2:3], v[220:221], 0, s[42:43]
	global_load_lds_dwordx4 v[2:3], off
	v_lshl_add_u64 v[2:3], v[222:223], 0, s[38:39]
	s_mov_b32 m0, s78
	s_nop 0
	global_load_lds_dwordx4 v[2:3], off
	s_waitcnt vmcnt(2)
	s_waitcnt lgkmcnt(0)
	s_barrier
	ds_read_b128 v[22:25], v243 offset:32768
	ds_read_b128 v[18:21], v242 offset:32768
	ds_read_b128 v[34:37], v242 offset:36864
	ds_read_b128 v[38:41], v243 offset:36864
	v_mov_b64_e32 v[2:3], s[8:9]
	v_mov_b64_e32 v[4:5], s[10:11]
	v_mov_b64_e32 v[6:7], s[12:13]
	v_mov_b64_e32 v[8:9], s[14:15]
	v_mov_b64_e32 v[10:11], s[16:17]
	v_mov_b64_e32 v[12:13], s[18:19]
	v_mov_b64_e32 v[14:15], s[20:21]
	v_mov_b64_e32 v[16:17], s[22:23]
	s_nop 1
	s_waitcnt vmcnt(0) lgkmcnt(0)
	v_mfma_scale_f32_32x32x64_f8f6f4 v[18:33], v[18:25], v[176:183], v[2:17], v240, v239 op_sel_hi:[0,0,0]
	s_xor_b64 s[48:49], s[54:55], -1
	s_add_u32 s56, s56, s36
	s_addc_u32 s57, s57, 0
	v_lshl_add_u64 v[224:225], v[216:217], 0, s[58:59]
	v_lshl_add_u64 v[226:227], v[218:219], 0, s[56:57]
	s_mov_b32 s45, 0
	s_mov_b32 s47, 0
	v_mfma_scale_f32_32x32x64_f8f6f4 v[2:17], v[34:41], v[176:183], v[2:17], v240, v239 op_sel_hi:[0,0,0]
	ds_read_b128 v[38:41], v245 offset:32768
	ds_read_b128 v[34:37], v244 offset:32768
	ds_read_b128 v[42:45], v244 offset:36864
	ds_read_b128 v[46:49], v245 offset:36864
	s_waitcnt lgkmcnt(2)
	v_mfma_scale_f32_32x32x64_f8f6f4 v[18:33], v[34:41], v[184:191], v[18:33], v240, v239 op_sel_hi:[0,0,0]
	s_waitcnt lgkmcnt(0)
	v_mfma_scale_f32_32x32x64_f8f6f4 v[2:17], v[42:49], v[184:191], v[2:17], v240, v239 op_sel_hi:[0,0,0]
	s_nop 15
	s_nop 1
	v_max_f32_e32 v1, v19, v19
	v_max_f32_e32 v34, v18, v18
	v_max_f32_e32 v1, v34, v1
	v_max3_f32 v1, v1, v20, v21
	v_max3_f32 v1, v1, v22, v23
	v_max3_f32 v1, v1, v24, v25
	v_max3_f32 v1, v1, v26, v27
	v_max3_f32 v1, v1, v28, v29
	v_max3_f32 v1, v1, v30, v31
	v_max3_f32 v1, v1, v32, v33
	v_max3_f32 v1, v1, v2, v3
	v_max3_f32 v1, v1, v4, v5
	v_max3_f32 v1, v1, v6, v7
	v_max3_f32 v1, v1, v8, v9
	v_max3_f32 v1, v1, v10, v11
	v_max3_f32 v1, v1, v12, v13
	v_max3_f32 v1, v1, v14, v15
	v_max3_f32 v1, v1, v16, v17
	v_mov_b32_e32 v34, v1
	s_nop 1
	v_permlane32_swap_b32_e32 v1, v34
	v_max_f32_e32 v34, v34, v34
	v_max_f32_e32 v1, v1, v1
	v_max_f32_e32 v1, v1, v34
	v_add_f32_e32 v1, 0xc0a00000, v1
	v_sub_f32_e32 v18, v18, v1
	v_sub_f32_e32 v19, v19, v1
	v_sub_f32_e32 v20, v20, v1
	v_sub_f32_e32 v21, v21, v1
	v_sub_f32_e32 v22, v22, v1
	v_sub_f32_e32 v23, v23, v1
	v_sub_f32_e32 v24, v24, v1
	v_sub_f32_e32 v25, v25, v1
	v_sub_f32_e32 v26, v26, v1
	v_sub_f32_e32 v27, v27, v1
	v_sub_f32_e32 v28, v28, v1
	v_sub_f32_e32 v29, v29, v1
	v_sub_f32_e32 v30, v30, v1
	v_sub_f32_e32 v31, v31, v1
	v_sub_f32_e32 v32, v32, v1
	v_sub_f32_e32 v33, v33, v1
	v_exp_f32_e32 v144, v18
	v_exp_f32_e32 v145, v19
	v_exp_f32_e32 v146, v20
	v_exp_f32_e32 v147, v21
	v_exp_f32_e32 v148, v22
	v_exp_f32_e32 v149, v23
	v_exp_f32_e32 v150, v24
	v_exp_f32_e32 v151, v25
	v_exp_f32_e32 v152, v26
	v_exp_f32_e32 v153, v27
	v_exp_f32_e32 v154, v28
	v_exp_f32_e32 v155, v29
	v_exp_f32_e32 v156, v30
	v_exp_f32_e32 v157, v31
	v_exp_f32_e32 v158, v32
	v_exp_f32_e32 v159, v33
	v_sub_f32_e32 v125, v15, v1
	v_sub_f32_e32 v124, v14, v1
	v_mov_b32_e32 v14, v0
	v_mov_b32_e32 v15, v0
	v_sub_f32_e32 v96, 0x40a00000, v1
	v_sub_f32_e32 v127, v17, v1
	v_sub_f32_e32 v126, v16, v1
	v_sub_f32_e32 v123, v13, v1
	v_sub_f32_e32 v122, v12, v1
	v_sub_f32_e32 v121, v11, v1
	v_sub_f32_e32 v120, v10, v1
	v_sub_f32_e32 v119, v9, v1
	v_sub_f32_e32 v118, v8, v1
	v_sub_f32_e32 v117, v7, v1
	v_sub_f32_e32 v116, v6, v1
	v_sub_f32_e32 v115, v5, v1
	v_sub_f32_e32 v114, v4, v1
	v_sub_f32_e32 v113, v3, v1
	v_sub_f32_e32 v112, v2, v1
	v_mov_b32_e32 v1, v0
	v_mov_b32_e32 v2, v0
	v_mov_b32_e32 v3, v0
	v_mov_b32_e32 v4, v0
	v_mov_b32_e32 v5, v0
	v_mov_b32_e32 v6, v0
	v_mov_b32_e32 v7, v0
	v_mov_b32_e32 v8, v0
	v_mov_b32_e32 v9, v0
	v_mov_b32_e32 v10, v0
	v_mov_b32_e32 v11, v0
	v_mov_b32_e32 v12, v0
	v_mov_b32_e32 v13, v0
	v_mov_b64_e32 v[78:79], v[14:15]
	v_mov_b64_e32 v[62:63], v[14:15]
	v_mov_b64_e32 v[46:47], v[14:15]
	v_mov_b64_e32 v[30:31], v[14:15]
	v_mov_b64_e32 v[94:95], v[14:15]
	v_mov_b32_e32 v97, v96
	v_mov_b32_e32 v98, v96
	v_mov_b32_e32 v99, v96
	v_mov_b32_e32 v100, v96
	v_mov_b32_e32 v101, v96
	v_mov_b32_e32 v102, v96
	v_mov_b32_e32 v103, v96
	v_mov_b32_e32 v104, v96
	v_mov_b32_e32 v105, v96
	v_mov_b32_e32 v106, v96
	v_mov_b32_e32 v107, v96
	v_mov_b32_e32 v108, v96
	v_mov_b32_e32 v109, v96
	v_mov_b32_e32 v110, v96
	v_mov_b32_e32 v111, v96
	v_mov_b64_e32 v[76:77], v[12:13]
	v_mov_b64_e32 v[74:75], v[10:11]
	v_mov_b64_e32 v[72:73], v[8:9]
	v_mov_b64_e32 v[70:71], v[6:7]
	v_mov_b64_e32 v[68:69], v[4:5]
	v_mov_b64_e32 v[66:67], v[2:3]
	v_mov_b64_e32 v[64:65], v[0:1]
	v_mov_b64_e32 v[60:61], v[12:13]
	v_mov_b64_e32 v[58:59], v[10:11]
	v_mov_b64_e32 v[56:57], v[8:9]
	v_mov_b64_e32 v[54:55], v[6:7]
	v_mov_b64_e32 v[52:53], v[4:5]
	v_mov_b64_e32 v[50:51], v[2:3]
	v_mov_b64_e32 v[48:49], v[0:1]
	v_mov_b64_e32 v[44:45], v[12:13]
	v_mov_b64_e32 v[42:43], v[10:11]
	v_mov_b64_e32 v[40:41], v[8:9]
	v_mov_b64_e32 v[38:39], v[6:7]
	v_mov_b64_e32 v[36:37], v[4:5]
	v_mov_b64_e32 v[34:35], v[2:3]
	v_mov_b64_e32 v[32:33], v[0:1]
	v_mov_b64_e32 v[28:29], v[12:13]
	v_mov_b64_e32 v[26:27], v[10:11]
	v_mov_b64_e32 v[24:25], v[8:9]
	v_mov_b64_e32 v[22:23], v[6:7]
	v_mov_b64_e32 v[20:21], v[4:5]
	v_mov_b64_e32 v[18:19], v[2:3]
	v_mov_b64_e32 v[16:17], v[0:1]
	v_mov_b64_e32 v[92:93], v[12:13]
	v_mov_b64_e32 v[90:91], v[10:11]
	v_mov_b64_e32 v[88:89], v[8:9]
	v_mov_b64_e32 v[86:87], v[6:7]
	v_mov_b64_e32 v[84:85], v[4:5]
	v_mov_b64_e32 v[82:83], v[2:3]
	v_mov_b64_e32 v[80:81], v[0:1]
	s_cmp_lg_u32 s92, 0
	s_cbranch_scc1 .LgB_374
	s_branch .LBB0_374

; #define SBAR() __builtin_amdgcn_sched_barrier(0)
; #define DMA(slot, t) do { \
;     __builtin_amdgcn_global_load_lds((const unsigned*)(Kg + (long)(t) * (64 * 256)), (LAS unsigned*)(L3 + K_OFF + (slot) * SHM_T + wid * 1024), 16, 0, 0); \
;     __builtin_amdgcn_global_load_lds((const unsigned*)(Vg + (long)(t) * 8192), (LAS unsigned*)(L3 + (slot) * SHM_T + wid * 1024), 16, 0, 0); } while (0)
; #define BAR() do { asm volatile("s_waitcnt lgkmcnt(0)" ::: "memory"); __builtin_amdgcn_s_barrier(); asm volatile("" ::: "memory"); } while (0)
; #define WAITV(n) asm volatile("s_waitcnt vmcnt(" #n ")" ::: "memory")
; #define RESC(a) do { if (__any((a) < 1.f)) { if (hi == 0) al_l[r32] = (a); asm volatile("s_waitcnt lgkmcnt(0)" ::: "memory"); \
;     for (int r = 0; r < 16; ++r) { const float a_ = al_l[crow(r, hi)]; ls[r] *= a_; for (int d = 0; d < 4; ++d) o[d][r] *= a_; } } } while (0)
; #define QKT(P0, P1, b) qkt(P0, P1, nm, K_lds + (b) * SHM_T, qr, ko, c00, c01, c10, c11)
; #define PIPE1() do { SGB(0x100, 8); SGB(0x400, 4); SGB(0x008, 1); SGB(0x400, 4); SGB(0x008, 1); SGB(0x400, 4); SGB(0x008, 1); SGB(0x400, 4); SGB(0x008, 1); } while (0)
; #define HALF2(Y0, Y1, alY, b) do { PVL(b); const float pm_ = max32(Y0, Y1); adjustSM(Y0, Y1, nm, alY, pm_); SBAR(); \
;     PVM(); exp16(Y0); asm volatile("" : "+v"(Y0)); \
;     SGB(0x008, 1); SGB(0x400, 3); SGB(0x008, 1); SGB(0x400, 3); SGB(0x008, 1); SGB(0x400, 3); SGB(0x008, 1); SGB(0x400, 3); SGB(0x008, 1); SGB(0x400, 4); SBAR(); } while (0)
; __device__ __forceinline__ void body(const unsigned char* Q8b, const unsigned char* K8h, const unsigned char* VT8h, const bf16_t* Gb, bf16_t* Ob, int seq, char* lds, const int wid, ...
;     ...
;   for (int i = 0; i + 2 < NT; i += 2) {
;     SBAR(); QKT(pB0, pB1, (s0 + 1) & 3);
;     finishSM(pA0, pA1, pf); PIPE1(); SBAR();
;     DMA((s0 + 3) & 3, i + 3);
;     SBAR();
;     HALF2(pB0, pB1, alB, s0);
;     WAITV(2);
;     RESC(alB); BAR();
.LBB0_373:
	s_waitcnt lgkmcnt(0)
	s_barrier
	s_add_i32 s45, s45, 2
	s_add_u32 s100, s100, 0x4000
	s_addc_u32 s101, s101, 0
	s_add_u32 s98, s98, 0x8000
	s_addc_u32 s99, s99, 0
	s_cmpk_gt_u32 s45, 0x7d
	s_cbranch_scc1 .LBB0_385
	s_branch .Lc2_374
.LBB0_374:
	ds_read_b128 v[2:5], v242 offset:40960
	ds_read_b128 v[6:9], v243 offset:40960
	ds_read_b128 v[128:131], v242 offset:45056
	ds_read_b128 v[132:135], v243 offset:45056
	ds_read_b128 v[194:197], v244 offset:40960
	ds_read_b128 v[198:201], v245 offset:40960
	ds_read_b128 v[246:249], v244 offset:45056
	ds_read_b128 v[250:253], v245 offset:45056
	v_exp_f32_e32 v1, v112
	v_exp_f32_e32 v10, v113
	v_exp_f32_e32 v11, v114
	v_exp_f32_e32 v12, v115
	s_waitcnt lgkmcnt(6)
	s_setprio 1
	v_mfma_scale_f32_32x32x64_f8f6f4 v[160:175], v[2:9], v[176:183], v[96:111], v240, v239 op_sel_hi:[0,0,0]
	v_exp_f32_e32 v6, v116
	v_exp_f32_e32 v7, v117
	v_exp_f32_e32 v8, v118
	v_exp_f32_e32 v9, v119
	v_cvt_pk_fp8_f32 v5, v6, v7
	v_cvt_pk_fp8_f32 v3, v1, v10
	v_cvt_pk_fp8_f32 v5, v8, v9 op_sel:[0,0,1]
	s_waitcnt lgkmcnt(4)
	v_mfma_scale_f32_32x32x64_f8f6f4 v[128:143], v[128:135], v[176:183], v[96:111], v240, v239 op_sel_hi:[0,0,0]
	v_exp_f32_e32 v13, v120
	v_exp_f32_e32 v14, v121
	v_exp_f32_e32 v15, v122
	v_exp_f32_e32 v112, v123
	v_cvt_pk_fp8_f32 v2, v144, v145
	v_cvt_pk_fp8_f32 v4, v148, v149
	v_cvt_pk_fp8_f32 v6, v152, v153
	v_cvt_pk_fp8_f32 v7, v13, v14
	v_cvt_pk_fp8_f32 v8, v156, v157
	v_cvt_pk_fp8_f32 v2, v146, v147 op_sel:[0,0,1]
	v_cvt_pk_fp8_f32 v3, v11, v12 op_sel:[0,0,1]
	v_cvt_pk_fp8_f32 v4, v150, v151 op_sel:[0,0,1]
	v_cvt_pk_fp8_f32 v6, v154, v155 op_sel:[0,0,1]
	v_cvt_pk_fp8_f32 v7, v15, v112 op_sel:[0,0,1]
	v_cvt_pk_fp8_f32 v8, v158, v159 op_sel:[0,0,1]
	s_waitcnt lgkmcnt(2)
	v_mfma_scale_f32_32x32x64_f8f6f4 v[160:175], v[194:201], v[184:191], v[160:175], v240, v239 op_sel_hi:[0,0,0]
	v_exp_f32_e32 v113, v124
	v_exp_f32_e32 v114, v125
	v_exp_f32_e32 v1, v126
	v_exp_f32_e32 v10, v127
	v_cvt_pk_fp8_f32 v9, v113, v114
	s_nop 0
	v_cvt_pk_fp8_f32 v9, v1, v10 op_sel:[0,0,1]
	s_waitcnt lgkmcnt(0)
	v_mfma_scale_f32_32x32x64_f8f6f4 v[128:143], v[246:253], v[184:191], v[128:143], v240, v239 op_sel_hi:[0,0,0]
	s_setprio 0
	s_add_i32 m0, s68, 0xe000
	s_nop 0
	global_load_lds_dwordx4 v192, s[98:99]
	s_add_i32 m0, s68, 0x6000
	s_nop 0
	global_load_lds_dwordx4 v193, s[100:101]
	ds_read_b128 v[194:197], v254
	ds_read_b128 v[148:151], v254 offset:2048
	ds_read_b128 v[198:201], v255
	ds_read_b128 v[152:155], v255 offset:2048
	ds_read_b128 v[120:123], v254 offset:4096
	ds_read_b128 v[112:115], v254 offset:6144
	ds_read_b128 v[124:127], v255 offset:4096
	ds_read_b128 v[116:119], v255 offset:6144
	v_max_f32_e32 v1, v160, v161
	v_max3_f32 v1, v1, v162, v163
	v_max3_f32 v1, v1, v164, v165
	v_max3_f32 v1, v1, v166, v167
	v_max3_f32 v1, v1, v168, v169
	v_max3_f32 v1, v1, v170, v171
	v_max3_f32 v1, v1, v172, v173
	v_max3_f32 v1, v1, v174, v175
	v_max3_f32 v1, v1, v128, v129
	v_max3_f32 v1, v1, v130, v131
	v_max3_f32 v1, v1, v132, v133
	v_max3_f32 v1, v1, v134, v135
	v_max3_f32 v1, v1, v136, v137
	v_max3_f32 v1, v1, v138, v139
	v_max3_f32 v1, v1, v140, v141
	v_max3_f32 v1, v1, v142, v143
	v_cmp_lt_f32_e32 vcc, s80, v1
	s_cbranch_vccnz .LBB0_383
.LBB0_375:
	s_waitcnt lgkmcnt(0)
	v_mfma_scale_f32_32x32x64_f8f6f4 v[64:79], v[2:9], v[194:201], v[64:79], v240, v240 op_sel_hi:[0,0,0]
	v_exp_f32_e32 v144, v160
	v_exp_f32_e32 v145, v161
	v_exp_f32_e32 v146, v162
	v_mfma_scale_f32_32x32x64_f8f6f4 v[48:63], v[2:9], v[148:155], v[48:63], v240, v240 op_sel_hi:[0,0,0]
	v_exp_f32_e32 v147, v163
	v_exp_f32_e32 v148, v164
	v_exp_f32_e32 v149, v165
	v_mfma_scale_f32_32x32x64_f8f6f4 v[32:47], v[2:9], v[120:127], v[32:47], v240, v240 op_sel_hi:[0,0,0]
	v_exp_f32_e32 v150, v166
	v_exp_f32_e32 v151, v167
	v_exp_f32_e32 v152, v168
	v_mfma_scale_f32_32x32x64_f8f6f4 v[16:31], v[2:9], v[112:119], v[16:31], v240, v240 op_sel_hi:[0,0,0]
	v_exp_f32_e32 v153, v169
	v_exp_f32_e32 v154, v170
	v_exp_f32_e32 v155, v171
	v_mfma_scale_f32_32x32x64_f8f6f4 v[80:95], v[2:9], v[228:235], v[80:95], v240, v240 op_sel_hi:[0,0,0]
	v_exp_f32_e32 v156, v172
	v_exp_f32_e32 v157, v173
	v_exp_f32_e32 v158, v174
	v_exp_f32_e32 v159, v175
	s_waitcnt vmcnt(2)
	s_cmp_eq_u32 s93, 0
	s_cbranch_scc1 .LBB0_379
	s_mov_b32 s93, 0
	s_and_saveexec_b64 s[56:57], s[4:5]
	ds_write_b32 v236, v1 offset:128
	s_or_b64 exec, exec, s[56:57]
	s_waitcnt lgkmcnt(0)
	v_add_u32_e32 v1, s67, v237
	ds_read_b128 v[2:5], v1 offset:224
	ds_read_b128 v[6:9], v1 offset:192
	ds_read_b128 v[10:13], v1 offset:160
	ds_read_b128 v[112:115], v1 offset:128
	s_waitcnt lgkmcnt(0)
	v_pk_mul_f32 v[76:77], v[76:77], v[2:3]
	v_pk_mul_f32 v[72:73], v[72:73], v[6:7]
	v_pk_mul_f32 v[68:69], v[68:69], v[10:11]
	v_pk_mul_f32 v[78:79], v[78:79], v[4:5]
	v_pk_mul_f32 v[74:75], v[74:75], v[8:9]
	v_pk_mul_f32 v[70:71], v[70:71], v[12:13]
	v_pk_mul_f32 v[66:67], v[66:67], v[114:115]
	v_pk_mul_f32 v[64:65], v[64:65], v[112:113]
	v_pk_mul_f32 v[60:61], v[60:61], v[2:3]
	v_pk_mul_f32 v[56:57], v[56:57], v[6:7]
	v_pk_mul_f32 v[52:53], v[52:53], v[10:11]
	v_pk_mul_f32 v[62:63], v[62:63], v[4:5]
	v_pk_mul_f32 v[58:59], v[58:59], v[8:9]
	v_pk_mul_f32 v[54:55], v[54:55], v[12:13]
	v_pk_mul_f32 v[50:51], v[50:51], v[114:115]
	v_pk_mul_f32 v[48:49], v[48:49], v[112:113]
	v_pk_mul_f32 v[44:45], v[44:45], v[2:3]
	v_pk_mul_f32 v[40:41], v[40:41], v[6:7]
	v_pk_mul_f32 v[36:37], v[36:37], v[10:11]
	v_pk_mul_f32 v[46:47], v[46:47], v[4:5]
	v_pk_mul_f32 v[42:43], v[42:43], v[8:9]
	v_pk_mul_f32 v[38:39], v[38:39], v[12:13]
	v_pk_mul_f32 v[34:35], v[34:35], v[114:115]
	v_pk_mul_f32 v[32:33], v[32:33], v[112:113]
	v_pk_mul_f32 v[28:29], v[28:29], v[2:3]
	v_pk_mul_f32 v[24:25], v[24:25], v[6:7]
	v_pk_mul_f32 v[20:21], v[20:21], v[10:11]
	v_pk_mul_f32 v[30:31], v[30:31], v[4:5]
	v_pk_mul_f32 v[26:27], v[26:27], v[8:9]
	v_pk_mul_f32 v[22:23], v[22:23], v[12:13]
	v_pk_mul_f32 v[18:19], v[18:19], v[114:115]
	v_pk_mul_f32 v[16:17], v[16:17], v[112:113]
	v_pk_mul_f32 v[92:93], v[92:93], v[2:3]
	v_pk_mul_f32 v[88:89], v[88:89], v[6:7]
	v_pk_mul_f32 v[84:85], v[84:85], v[10:11]
	v_pk_mul_f32 v[94:95], v[94:95], v[4:5]
	v_pk_mul_f32 v[90:91], v[90:91], v[8:9]
	v_pk_mul_f32 v[86:87], v[86:87], v[12:13]
	v_pk_mul_f32 v[82:83], v[82:83], v[114:115]
	v_pk_mul_f32 v[80:81], v[80:81], v[112:113]
; #define SBAR() __builtin_amdgcn_sched_barrier(0)
; #define DMA(slot, t) do { \
;     __builtin_amdgcn_global_load_lds((const unsigned*)(Kg + (long)(t) * (64 * 256)), (LAS unsigned*)(L3 + K_OFF + (slot) * SHM_T + wid * 1024), 16, 0, 0); \
;     __builtin_amdgcn_global_load_lds((const unsigned*)(Vg + (long)(t) * 8192), (LAS unsigned*)(L3 + (slot) * SHM_T + wid * 1024), 16, 0, 0); } while (0)
; #define BAR() do { asm volatile("s_waitcnt lgkmcnt(0)" ::: "memory"); __builtin_amdgcn_s_barrier(); asm volatile("" ::: "memory"); } while (0)
; #define RESC(a) do { if (__any((a) < 1.f)) { if (hi == 0) al_l[r32] = (a); asm volatile("s_waitcnt lgkmcnt(0)" ::: "memory"); \
;     for (int r = 0; r < 16; ++r) { const float a_ = al_l[crow(r, hi)]; ls[r] *= a_; for (int d = 0; d < 4; ++d) o[d][r] *= a_; } } } while (0)
; #define QKT(P0, P1, b) qkt(P0, P1, nm, K_lds + (b) * SHM_T, qr, ko, c00, c01, c10, c11)
; #define PIPE1() do { SGB(0x100, 8); SGB(0x400, 4); SGB(0x008, 1); SGB(0x400, 4); SGB(0x008, 1); SGB(0x400, 4); SGB(0x008, 1); SGB(0x400, 4); SGB(0x008, 1); } while (0)
; #define HALF2(Y0, Y1, alY, b) do { PVL(b); const float pm_ = max32(Y0, Y1); adjustSM(Y0, Y1, nm, alY, pm_); SBAR(); \
;     PVM(); exp16(Y0); asm volatile("" : "+v"(Y0)); \
;     SGB(0x008, 1); SGB(0x400, 3); SGB(0x008, 1); SGB(0x400, 3); SGB(0x008, 1); SGB(0x400, 3); SGB(0x008, 1); SGB(0x400, 3); SGB(0x008, 1); SGB(0x400, 4); SBAR(); } while (0)
; __device__ __forceinline__ void body(const unsigned char* Q8b, const unsigned char* K8h, const unsigned char* VT8h, const bf16_t* Gb, bf16_t* Ob, int seq, char* lds, const int wid, ...
;     ...
;     RESC(alB); BAR();
;     SBAR(); QKT(pA0, pA1, (s0 + 2) & 3);
;     finishSM(pB0, pB1, pf); PIPE1(); SBAR();
;     { const int t4 = (i + 4 < NT) ? i + 4 : NT - 1; DMA(s0, t4); }
;     SBAR();
;     HALF2(pA0, pA1, alA, (s0 + 1) & 3);
.LBB0_379:
	s_waitcnt lgkmcnt(0)
	s_barrier
	ds_read_b128 v[2:5], v242 offset:49152
	ds_read_b128 v[6:9], v243 offset:49152
	ds_read_b128 v[112:115], v242 offset:53248
	ds_read_b128 v[116:119], v243 offset:53248
	ds_read_b128 v[194:197], v244 offset:49152
	ds_read_b128 v[198:201], v245 offset:49152
	ds_read_b128 v[246:249], v244 offset:53248
	ds_read_b128 v[250:253], v245 offset:53248
	v_exp_f32_e32 v1, v128
	v_exp_f32_e32 v10, v129
	v_exp_f32_e32 v11, v130
	v_exp_f32_e32 v12, v131
	s_waitcnt lgkmcnt(6)
	s_setprio 1
	v_mfma_scale_f32_32x32x64_f8f6f4 v[160:175], v[2:9], v[176:183], v[96:111], v240, v239 op_sel_hi:[0,0,0]
	v_exp_f32_e32 v6, v132
	v_exp_f32_e32 v7, v133
	v_exp_f32_e32 v8, v134
	v_exp_f32_e32 v9, v135
	v_cvt_pk_fp8_f32 v5, v6, v7
	v_cvt_pk_fp8_f32 v2, v144, v145
	v_cvt_pk_fp8_f32 v5, v8, v9 op_sel:[0,0,1]
	s_waitcnt lgkmcnt(4)
	v_mfma_scale_f32_32x32x64_f8f6f4 v[112:127], v[112:119], v[176:183], v[96:111], v240, v239 op_sel_hi:[0,0,0]
	v_exp_f32_e32 v13, v136
	v_exp_f32_e32 v14, v137
	v_exp_f32_e32 v15, v138
	v_exp_f32_e32 v128, v139
	v_cvt_pk_fp8_f32 v3, v1, v10
	v_cvt_pk_fp8_f32 v4, v148, v149
	v_cvt_pk_fp8_f32 v6, v152, v153
	v_cvt_pk_fp8_f32 v7, v13, v14
	v_cvt_pk_fp8_f32 v8, v156, v157
	v_cvt_pk_fp8_f32 v2, v146, v147 op_sel:[0,0,1]
	v_cvt_pk_fp8_f32 v3, v11, v12 op_sel:[0,0,1]
	v_cvt_pk_fp8_f32 v4, v150, v151 op_sel:[0,0,1]
	v_cvt_pk_fp8_f32 v6, v154, v155 op_sel:[0,0,1]
	v_cvt_pk_fp8_f32 v7, v15, v128 op_sel:[0,0,1]
	v_cvt_pk_fp8_f32 v8, v158, v159 op_sel:[0,0,1]
	s_waitcnt lgkmcnt(2)
	v_mfma_scale_f32_32x32x64_f8f6f4 v[160:175], v[194:201], v[184:191], v[160:175], v240, v239 op_sel_hi:[0,0,0]
	v_exp_f32_e32 v129, v140
	v_exp_f32_e32 v130, v141
	v_exp_f32_e32 v131, v142
	v_exp_f32_e32 v132, v143
	v_cvt_pk_fp8_f32 v9, v129, v130
	s_nop 0
	v_cvt_pk_fp8_f32 v9, v131, v132 op_sel:[0,0,1]
	s_waitcnt lgkmcnt(0)
	v_mfma_scale_f32_32x32x64_f8f6f4 v[112:127], v[246:253], v[184:191], v[112:127], v240, v239 op_sel_hi:[0,0,0]
	s_setprio 0
	s_min_u32 s36, s45, 0x7b
	s_add_i32 s56, s36, 4
	s_lshl_b32 s36, s56, 14
	s_add_i32 s57, s68, 0x0
	s_add_u32 s88, s94, s36
	s_addc_u32 s89, s95, 0
	s_add_i32 m0, s57, 0x8000
	s_lshl_b32 s36, s56, 13
	s_add_u32 s90, s96, s36
	s_addc_u32 s91, s97, 0
	global_load_lds_dwordx4 v192, s[88:89]
	s_mov_b32 m0, s57
	s_nop 0
	global_load_lds_dwordx4 v193, s[90:91]
	ds_read_b128 v[194:197], v254 offset:8192
	ds_read_b128 v[148:151], v254 offset:10240
	ds_read_b128 v[198:201], v255 offset:8192
	ds_read_b128 v[152:155], v255 offset:10240
	ds_read_b128 v[136:139], v254 offset:12288
	ds_read_b128 v[128:131], v254 offset:14336
	ds_read_b128 v[140:143], v255 offset:12288
	ds_read_b128 v[132:135], v255 offset:14336
	v_max_f32_e32 v1, v160, v161
	v_max3_f32 v1, v1, v162, v163
	v_max3_f32 v1, v1, v164, v165
	v_max3_f32 v1, v1, v166, v167
	v_max3_f32 v1, v1, v168, v169
	v_max3_f32 v1, v1, v170, v171
	v_max3_f32 v1, v1, v172, v173
	v_max3_f32 v1, v1, v174, v175
	v_max3_f32 v1, v1, v112, v113
	v_max3_f32 v1, v1, v114, v115
	v_max3_f32 v1, v1, v116, v117
	v_max3_f32 v1, v1, v118, v119
	v_max3_f32 v1, v1, v120, v121
	v_max3_f32 v1, v1, v122, v123
	v_max3_f32 v1, v1, v124, v125
	v_max3_f32 v1, v1, v126, v127
	v_cmp_lt_f32_e32 vcc, s80, v1
	s_cbranch_vccnz .LBB0_384

; #define SBAR() __builtin_amdgcn_sched_barrier(0)
; #define DMA(slot, t) do { \
;     __builtin_amdgcn_global_load_lds((const unsigned*)(Kg + (long)(t) * (64 * 256)), (LAS unsigned*)(L3 + K_OFF + (slot) * SHM_T + wid * 1024), 16, 0, 0); \
;     __builtin_amdgcn_global_load_lds((const unsigned*)(Vg + (long)(t) * 8192), (LAS unsigned*)(L3 + (slot) * SHM_T + wid * 1024), 16, 0, 0); } while (0)
; #define BAR() do { asm volatile("s_waitcnt lgkmcnt(0)" ::: "memory"); __builtin_amdgcn_s_barrier(); asm volatile("" ::: "memory"); } while (0)
; #define WAITV(n) asm volatile("s_waitcnt vmcnt(" #n ")" ::: "memory")
; #define RESC(a) do { if (__any((a) < 1.f)) { if (hi == 0) al_l[r32] = (a); asm volatile("s_waitcnt lgkmcnt(0)" ::: "memory"); \
;     for (int r = 0; r < 16; ++r) { const float a_ = al_l[crow(r, hi)]; ls[r] *= a_; for (int d = 0; d < 4; ++d) o[d][r] *= a_; } } } while (0)
; #define QKT(P0, P1, b) qkt(P0, P1, nm, K_lds + (b) * SHM_T, qr, ko, c00, c01, c10, c11)
; #define PIPE1() do { SGB(0x100, 8); SGB(0x400, 4); SGB(0x008, 1); SGB(0x400, 4); SGB(0x008, 1); SGB(0x400, 4); SGB(0x008, 1); SGB(0x400, 4); SGB(0x008, 1); } while (0)
; #define HALF2(Y0, Y1, alY, b) do { PVL(b); const float pm_ = max32(Y0, Y1); adjustSM(Y0, Y1, nm, alY, pm_); SBAR(); \
;     PVM(); exp16(Y0); asm volatile("" : "+v"(Y0)); \
;     SGB(0x008, 1); SGB(0x400, 3); SGB(0x008, 1); SGB(0x400, 3); SGB(0x008, 1); SGB(0x400, 3); SGB(0x008, 1); SGB(0x400, 3); SGB(0x008, 1); SGB(0x400, 4); SBAR(); } while (0)
; __device__ __forceinline__ void body(const unsigned char* Q8b, const unsigned char* K8h, const unsigned char* VT8h, const bf16_t* Gb, bf16_t* Ob, int seq, char* lds, const int wid, ...
;     ...
;     SBAR(); QKT(pB0, pB1, (s0 + 1) & 3);
;     finishSM(pA0, pA1, pf); PIPE1(); SBAR();
;     DMA((s0 + 3) & 3, i + 3);
;     SBAR();
;     HALF2(pB0, pB1, alB, s0);
;     WAITV(2);
;     RESC(alB); BAR();
.Lc2_374:
	ds_read_b128 v[2:5], v242 offset:57344
	ds_read_b128 v[6:9], v243 offset:57344
	ds_read_b128 v[128:131], v242 offset:61440
	ds_read_b128 v[132:135], v243 offset:61440
	ds_read_b128 v[194:197], v244 offset:57344
	ds_read_b128 v[198:201], v245 offset:57344
	ds_read_b128 v[246:249], v244 offset:61440
	ds_read_b128 v[250:253], v245 offset:61440
	v_exp_f32_e32 v1, v112
	v_exp_f32_e32 v10, v113
	v_exp_f32_e32 v11, v114
	v_exp_f32_e32 v12, v115
	s_waitcnt lgkmcnt(6)
	s_setprio 1
	v_mfma_scale_f32_32x32x64_f8f6f4 v[160:175], v[2:9], v[176:183], v[96:111], v240, v239 op_sel_hi:[0,0,0]
	v_exp_f32_e32 v6, v116
	v_exp_f32_e32 v7, v117
	v_exp_f32_e32 v8, v118
	v_exp_f32_e32 v9, v119
	v_cvt_pk_fp8_f32 v5, v6, v7
	v_cvt_pk_fp8_f32 v3, v1, v10
	v_cvt_pk_fp8_f32 v5, v8, v9 op_sel:[0,0,1]
	s_waitcnt lgkmcnt(4)
	v_mfma_scale_f32_32x32x64_f8f6f4 v[128:143], v[128:135], v[176:183], v[96:111], v240, v239 op_sel_hi:[0,0,0]
	v_exp_f32_e32 v13, v120
	v_exp_f32_e32 v14, v121
	v_exp_f32_e32 v15, v122
	v_exp_f32_e32 v112, v123
	v_cvt_pk_fp8_f32 v2, v144, v145
	v_cvt_pk_fp8_f32 v4, v148, v149
	v_cvt_pk_fp8_f32 v6, v152, v153
	v_cvt_pk_fp8_f32 v7, v13, v14
	v_cvt_pk_fp8_f32 v8, v156, v157
	v_cvt_pk_fp8_f32 v2, v146, v147 op_sel:[0,0,1]
	v_cvt_pk_fp8_f32 v3, v11, v12 op_sel:[0,0,1]
	v_cvt_pk_fp8_f32 v4, v150, v151 op_sel:[0,0,1]
	v_cvt_pk_fp8_f32 v6, v154, v155 op_sel:[0,0,1]
	v_cvt_pk_fp8_f32 v7, v15, v112 op_sel:[0,0,1]
	v_cvt_pk_fp8_f32 v8, v158, v159 op_sel:[0,0,1]
	s_waitcnt lgkmcnt(2)
	v_mfma_scale_f32_32x32x64_f8f6f4 v[160:175], v[194:201], v[184:191], v[160:175], v240, v239 op_sel_hi:[0,0,0]
	v_exp_f32_e32 v113, v124
	v_exp_f32_e32 v114, v125
	v_exp_f32_e32 v1, v126
	v_exp_f32_e32 v10, v127
	v_cvt_pk_fp8_f32 v9, v113, v114
	s_nop 0
	v_cvt_pk_fp8_f32 v9, v1, v10 op_sel:[0,0,1]
	s_waitcnt lgkmcnt(0)
	v_mfma_scale_f32_32x32x64_f8f6f4 v[128:143], v[246:253], v[184:191], v[128:143], v240, v239 op_sel_hi:[0,0,0]
	s_setprio 0
	s_add_i32 m0, s68, 0xa000
	s_nop 0
	global_load_lds_dwordx4 v192, s[98:99]
	s_add_i32 m0, s68, 0x2000
	s_nop 0
	global_load_lds_dwordx4 v193, s[100:101]
	ds_read_b128 v[194:197], v254 offset:16384
	ds_read_b128 v[148:151], v254 offset:18432
	ds_read_b128 v[198:201], v255 offset:16384
	ds_read_b128 v[152:155], v255 offset:18432
	ds_read_b128 v[120:123], v254 offset:20480
	ds_read_b128 v[112:115], v254 offset:22528
	ds_read_b128 v[124:127], v255 offset:20480
	ds_read_b128 v[116:119], v255 offset:22528
	v_max_f32_e32 v1, v160, v161
	v_max3_f32 v1, v1, v162, v163
	v_max3_f32 v1, v1, v164, v165
	v_max3_f32 v1, v1, v166, v167
	v_max3_f32 v1, v1, v168, v169
	v_max3_f32 v1, v1, v170, v171
	v_max3_f32 v1, v1, v172, v173
	v_max3_f32 v1, v1, v174, v175
	v_max3_f32 v1, v1, v128, v129
	v_max3_f32 v1, v1, v130, v131
	v_max3_f32 v1, v1, v132, v133
	v_max3_f32 v1, v1, v134, v135
	v_max3_f32 v1, v1, v136, v137
	v_max3_f32 v1, v1, v138, v139
	v_max3_f32 v1, v1, v140, v141
	v_max3_f32 v1, v1, v142, v143
	v_cmp_lt_f32_e32 vcc, s80, v1
	s_cbranch_vccnz .Lc2_383
.Lc2_375:
	s_waitcnt lgkmcnt(0)
	v_mfma_scale_f32_32x32x64_f8f6f4 v[64:79], v[2:9], v[194:201], v[64:79], v240, v240 op_sel_hi:[0,0,0]
	v_exp_f32_e32 v144, v160
	v_exp_f32_e32 v145, v161
	v_exp_f32_e32 v146, v162
	v_mfma_scale_f32_32x32x64_f8f6f4 v[48:63], v[2:9], v[148:155], v[48:63], v240, v240 op_sel_hi:[0,0,0]
	v_exp_f32_e32 v147, v163
	v_exp_f32_e32 v148, v164
	v_exp_f32_e32 v149, v165
	v_mfma_scale_f32_32x32x64_f8f6f4 v[32:47], v[2:9], v[120:127], v[32:47], v240, v240 op_sel_hi:[0,0,0]
	v_exp_f32_e32 v150, v166
	v_exp_f32_e32 v151, v167
	v_exp_f32_e32 v152, v168
	v_mfma_scale_f32_32x32x64_f8f6f4 v[16:31], v[2:9], v[112:119], v[16:31], v240, v240 op_sel_hi:[0,0,0]
	v_exp_f32_e32 v153, v169
	v_exp_f32_e32 v154, v170
	v_exp_f32_e32 v155, v171
	v_mfma_scale_f32_32x32x64_f8f6f4 v[80:95], v[2:9], v[228:235], v[80:95], v240, v240 op_sel_hi:[0,0,0]
	v_exp_f32_e32 v156, v172
	v_exp_f32_e32 v157, v173
	v_exp_f32_e32 v158, v174
	v_exp_f32_e32 v159, v175
	s_waitcnt vmcnt(2)
	s_cmp_eq_u32 s93, 0
	s_cbranch_scc1 .Lc2_379
	s_mov_b32 s93, 0
	s_and_saveexec_b64 s[56:57], s[4:5]
	ds_write_b32 v236, v1 offset:128
	s_or_b64 exec, exec, s[56:57]
	s_waitcnt lgkmcnt(0)
	v_add_u32_e32 v1, s67, v237
	ds_read_b128 v[2:5], v1 offset:224
	ds_read_b128 v[6:9], v1 offset:192
	ds_read_b128 v[10:13], v1 offset:160
	ds_read_b128 v[112:115], v1 offset:128
	s_waitcnt lgkmcnt(0)
	v_pk_mul_f32 v[76:77], v[76:77], v[2:3]
	v_pk_mul_f32 v[72:73], v[72:73], v[6:7]
	v_pk_mul_f32 v[68:69], v[68:69], v[10:11]
	v_pk_mul_f32 v[78:79], v[78:79], v[4:5]
	v_pk_mul_f32 v[74:75], v[74:75], v[8:9]
	v_pk_mul_f32 v[70:71], v[70:71], v[12:13]
	v_pk_mul_f32 v[66:67], v[66:67], v[114:115]
	v_pk_mul_f32 v[64:65], v[64:65], v[112:113]
	v_pk_mul_f32 v[60:61], v[60:61], v[2:3]
	v_pk_mul_f32 v[56:57], v[56:57], v[6:7]
	v_pk_mul_f32 v[52:53], v[52:53], v[10:11]
	v_pk_mul_f32 v[62:63], v[62:63], v[4:5]
	v_pk_mul_f32 v[58:59], v[58:59], v[8:9]
	v_pk_mul_f32 v[54:55], v[54:55], v[12:13]
	v_pk_mul_f32 v[50:51], v[50:51], v[114:115]
	v_pk_mul_f32 v[48:49], v[48:49], v[112:113]
	v_pk_mul_f32 v[44:45], v[44:45], v[2:3]
	v_pk_mul_f32 v[40:41], v[40:41], v[6:7]
	v_pk_mul_f32 v[36:37], v[36:37], v[10:11]
	v_pk_mul_f32 v[46:47], v[46:47], v[4:5]
	v_pk_mul_f32 v[42:43], v[42:43], v[8:9]
	v_pk_mul_f32 v[38:39], v[38:39], v[12:13]
	v_pk_mul_f32 v[34:35], v[34:35], v[114:115]
	v_pk_mul_f32 v[32:33], v[32:33], v[112:113]
	v_pk_mul_f32 v[28:29], v[28:29], v[2:3]
	v_pk_mul_f32 v[24:25], v[24:25], v[6:7]
	v_pk_mul_f32 v[20:21], v[20:21], v[10:11]
	v_pk_mul_f32 v[30:31], v[30:31], v[4:5]
	v_pk_mul_f32 v[26:27], v[26:27], v[8:9]
	v_pk_mul_f32 v[22:23], v[22:23], v[12:13]
	v_pk_mul_f32 v[18:19], v[18:19], v[114:115]
	v_pk_mul_f32 v[16:17], v[16:17], v[112:113]
	v_pk_mul_f32 v[92:93], v[92:93], v[2:3]
	v_pk_mul_f32 v[88:89], v[88:89], v[6:7]
	v_pk_mul_f32 v[84:85], v[84:85], v[10:11]
	v_pk_mul_f32 v[94:95], v[94:95], v[4:5]
	v_pk_mul_f32 v[90:91], v[90:91], v[8:9]
	v_pk_mul_f32 v[86:87], v[86:87], v[12:13]
	v_pk_mul_f32 v[82:83], v[82:83], v[114:115]
	v_pk_mul_f32 v[80:81], v[80:81], v[112:113]
; #define SBAR() __builtin_amdgcn_sched_barrier(0)
; #define DMA(slot, t) do { \
;     __builtin_amdgcn_global_load_lds((const unsigned*)(Kg + (long)(t) * (64 * 256)), (LAS unsigned*)(L3 + K_OFF + (slot) * SHM_T + wid * 1024), 16, 0, 0); \
;     __builtin_amdgcn_global_load_lds((const unsigned*)(Vg + (long)(t) * 8192), (LAS unsigned*)(L3 + (slot) * SHM_T + wid * 1024), 16, 0, 0); } while (0)
; #define BAR() do { asm volatile("s_waitcnt lgkmcnt(0)" ::: "memory"); __builtin_amdgcn_s_barrier(); asm volatile("" ::: "memory"); } while (0)
; #define RESC(a) do { if (__any((a) < 1.f)) { if (hi == 0) al_l[r32] = (a); asm volatile("s_waitcnt lgkmcnt(0)" ::: "memory"); \
;     for (int r = 0; r < 16; ++r) { const float a_ = al_l[crow(r, hi)]; ls[r] *= a_; for (int d = 0; d < 4; ++d) o[d][r] *= a_; } } } while (0)
; #define QKT(P0, P1, b) qkt(P0, P1, nm, K_lds + (b) * SHM_T, qr, ko, c00, c01, c10, c11)
; #define PIPE1() do { SGB(0x100, 8); SGB(0x400, 4); SGB(0x008, 1); SGB(0x400, 4); SGB(0x008, 1); SGB(0x400, 4); SGB(0x008, 1); SGB(0x400, 4); SGB(0x008, 1); } while (0)
; #define HALF2(Y0, Y1, alY, b) do { PVL(b); const float pm_ = max32(Y0, Y1); adjustSM(Y0, Y1, nm, alY, pm_); SBAR(); \
;     PVM(); exp16(Y0); asm volatile("" : "+v"(Y0)); \
;     SGB(0x008, 1); SGB(0x400, 3); SGB(0x008, 1); SGB(0x400, 3); SGB(0x008, 1); SGB(0x400, 3); SGB(0x008, 1); SGB(0x400, 3); SGB(0x008, 1); SGB(0x400, 4); SBAR(); } while (0)
; __device__ __forceinline__ void body(const unsigned char* Q8b, const unsigned char* K8h, const unsigned char* VT8h, const bf16_t* Gb, bf16_t* Ob, int seq, char* lds, const int wid, ...
;     ...
;     RESC(alB); BAR();
;     SBAR(); QKT(pA0, pA1, (s0 + 2) & 3);
;     finishSM(pB0, pB1, pf); PIPE1(); SBAR();
;     { const int t4 = (i + 4 < NT) ? i + 4 : NT - 1; DMA(s0, t4); }
;     SBAR();
;     HALF2(pA0, pA1, alA, (s0 + 1) & 3);
.Lc2_379:
	s_waitcnt lgkmcnt(0)
	s_barrier
	ds_read_b128 v[2:5], v242 offset:32768
	ds_read_b128 v[6:9], v243 offset:32768
	ds_read_b128 v[112:115], v242 offset:36864
	ds_read_b128 v[116:119], v243 offset:36864
	ds_read_b128 v[194:197], v244 offset:32768
	ds_read_b128 v[198:201], v245 offset:32768
	ds_read_b128 v[246:249], v244 offset:36864
	ds_read_b128 v[250:253], v245 offset:36864
	v_exp_f32_e32 v1, v128
	v_exp_f32_e32 v10, v129
	v_exp_f32_e32 v11, v130
	v_exp_f32_e32 v12, v131
	s_waitcnt lgkmcnt(6)
	s_setprio 1
	v_mfma_scale_f32_32x32x64_f8f6f4 v[160:175], v[2:9], v[176:183], v[96:111], v240, v239 op_sel_hi:[0,0,0]
	v_exp_f32_e32 v6, v132
	v_exp_f32_e32 v7, v133
	v_exp_f32_e32 v8, v134
	v_exp_f32_e32 v9, v135
	v_cvt_pk_fp8_f32 v5, v6, v7
	v_cvt_pk_fp8_f32 v2, v144, v145
	v_cvt_pk_fp8_f32 v5, v8, v9 op_sel:[0,0,1]
	s_waitcnt lgkmcnt(4)
	v_mfma_scale_f32_32x32x64_f8f6f4 v[112:127], v[112:119], v[176:183], v[96:111], v240, v239 op_sel_hi:[0,0,0]
	v_exp_f32_e32 v13, v136
	v_exp_f32_e32 v14, v137
	v_exp_f32_e32 v15, v138
	v_exp_f32_e32 v128, v139
	v_cvt_pk_fp8_f32 v3, v1, v10
	v_cvt_pk_fp8_f32 v4, v148, v149
	v_cvt_pk_fp8_f32 v6, v152, v153
	v_cvt_pk_fp8_f32 v7, v13, v14
	v_cvt_pk_fp8_f32 v8, v156, v157
	v_cvt_pk_fp8_f32 v2, v146, v147 op_sel:[0,0,1]
	v_cvt_pk_fp8_f32 v3, v11, v12 op_sel:[0,0,1]
	v_cvt_pk_fp8_f32 v4, v150, v151 op_sel:[0,0,1]
	v_cvt_pk_fp8_f32 v6, v154, v155 op_sel:[0,0,1]
	v_cvt_pk_fp8_f32 v7, v15, v128 op_sel:[0,0,1]
	v_cvt_pk_fp8_f32 v8, v158, v159 op_sel:[0,0,1]
	s_waitcnt lgkmcnt(2)
	v_mfma_scale_f32_32x32x64_f8f6f4 v[160:175], v[194:201], v[184:191], v[160:175], v240, v239 op_sel_hi:[0,0,0]
	v_exp_f32_e32 v129, v140
	v_exp_f32_e32 v130, v141
	v_exp_f32_e32 v131, v142
	v_exp_f32_e32 v132, v143
	v_cvt_pk_fp8_f32 v9, v129, v130
	s_nop 0
	v_cvt_pk_fp8_f32 v9, v131, v132 op_sel:[0,0,1]
	s_waitcnt lgkmcnt(0)
	v_mfma_scale_f32_32x32x64_f8f6f4 v[112:127], v[246:253], v[184:191], v[112:127], v240, v239 op_sel_hi:[0,0,0]
	s_setprio 0
	s_min_u32 s36, s45, 0x7b
	s_add_i32 s56, s36, 4
	s_lshl_b32 s36, s56, 14
	s_add_i32 s57, s68, 0x4000
	s_add_u32 s88, s94, s36
	s_addc_u32 s89, s95, 0
	s_add_i32 m0, s57, 0x8000
	s_lshl_b32 s36, s56, 13
	s_add_u32 s90, s96, s36
	s_addc_u32 s91, s97, 0
	global_load_lds_dwordx4 v192, s[88:89]
	s_mov_b32 m0, s57
	s_nop 0
	global_load_lds_dwordx4 v193, s[90:91]
	ds_read_b128 v[194:197], v254 offset:24576
	ds_read_b128 v[148:151], v254 offset:26624
	ds_read_b128 v[198:201], v255 offset:24576
	ds_read_b128 v[152:155], v255 offset:26624
	ds_read_b128 v[136:139], v254 offset:28672
	ds_read_b128 v[128:131], v254 offset:30720
	ds_read_b128 v[140:143], v255 offset:28672
	ds_read_b128 v[132:135], v255 offset:30720
	v_max_f32_e32 v1, v160, v161
	v_max3_f32 v1, v1, v162, v163
	v_max3_f32 v1, v1, v164, v165
	v_max3_f32 v1, v1, v166, v167
	v_max3_f32 v1, v1, v168, v169
	v_max3_f32 v1, v1, v170, v171
	v_max3_f32 v1, v1, v172, v173
	v_max3_f32 v1, v1, v174, v175
	v_max3_f32 v1, v1, v112, v113
	v_max3_f32 v1, v1, v114, v115
	v_max3_f32 v1, v1, v116, v117
	v_max3_f32 v1, v1, v118, v119
	v_max3_f32 v1, v1, v120, v121
	v_max3_f32 v1, v1, v122, v123
	v_max3_f32 v1, v1, v124, v125
	v_max3_f32 v1, v1, v126, v127
	v_cmp_lt_f32_e32 vcc, s80, v1
	s_cbranch_vccnz .Lc2_384

; #define BAR() do { asm volatile("s_waitcnt lgkmcnt(0)" ::: "memory"); __builtin_amdgcn_s_barrier(); asm volatile("" ::: "memory"); } while (0)
; #define WAITV(n) asm volatile("s_waitcnt vmcnt(" #n ")" ::: "memory")
; #define RESC(a) do { if (__any((a) < 1.f)) { if (hi == 0) al_l[r32] = (a); asm volatile("s_waitcnt lgkmcnt(0)" ::: "memory"); \
;     for (int r = 0; r < 16; ++r) { const float a_ = al_l[crow(r, hi)]; ls[r] *= a_; for (int d = 0; d < 4; ++d) o[d][r] *= a_; } } } while (0)
; __device__ __forceinline__ void body(const unsigned char* Q8b, const unsigned char* K8h, const unsigned char* VT8h, const bf16_t* Gb, bf16_t* Ob, int seq, char* lds, const int wid, ...
;     ...
;     WAITV(2);
;     RESC(alA); BAR();
;     s0 = (s0 + 2) & 3;
;   }
.LgB_372:
	s_or_b64 exec, exec, s[56:57]
	s_waitcnt lgkmcnt(0)
	v_add_u32_e32 v1, s67, v237
	ds_read_b128 v[2:5], v1 offset:224
	ds_read_b128 v[6:9], v1 offset:192
	ds_read_b128 v[10:13], v1 offset:160
	ds_read_b128 v[128:131], v1 offset:128
	s_waitcnt lgkmcnt(0)
	v_pk_mul_f32 v[76:77], v[76:77], v[2:3]
	v_pk_mul_f32 v[72:73], v[72:73], v[6:7]
	v_pk_mul_f32 v[68:69], v[68:69], v[10:11]
	v_pk_mul_f32 v[78:79], v[78:79], v[4:5]
	v_pk_mul_f32 v[74:75], v[74:75], v[8:9]
	v_pk_mul_f32 v[70:71], v[70:71], v[12:13]
	v_pk_mul_f32 v[66:67], v[66:67], v[130:131]
	v_pk_mul_f32 v[64:65], v[64:65], v[128:129]
	v_pk_mul_f32 v[60:61], v[60:61], v[2:3]
	v_pk_mul_f32 v[56:57], v[56:57], v[6:7]
	v_pk_mul_f32 v[52:53], v[52:53], v[10:11]
	v_pk_mul_f32 v[62:63], v[62:63], v[4:5]
	v_pk_mul_f32 v[58:59], v[58:59], v[8:9]
	v_pk_mul_f32 v[54:55], v[54:55], v[12:13]
	v_pk_mul_f32 v[50:51], v[50:51], v[130:131]
	v_pk_mul_f32 v[48:49], v[48:49], v[128:129]
	v_pk_mul_f32 v[44:45], v[44:45], v[2:3]
	v_pk_mul_f32 v[40:41], v[40:41], v[6:7]
	v_pk_mul_f32 v[36:37], v[36:37], v[10:11]
	v_pk_mul_f32 v[46:47], v[46:47], v[4:5]
	v_pk_mul_f32 v[42:43], v[42:43], v[8:9]
	v_pk_mul_f32 v[38:39], v[38:39], v[12:13]
	v_pk_mul_f32 v[34:35], v[34:35], v[130:131]
	v_pk_mul_f32 v[32:33], v[32:33], v[128:129]
	v_pk_mul_f32 v[28:29], v[28:29], v[2:3]
	v_pk_mul_f32 v[24:25], v[24:25], v[6:7]
	v_pk_mul_f32 v[20:21], v[20:21], v[10:11]
	v_pk_mul_f32 v[30:31], v[30:31], v[4:5]
	v_pk_mul_f32 v[26:27], v[26:27], v[8:9]
	v_pk_mul_f32 v[22:23], v[22:23], v[12:13]
	v_pk_mul_f32 v[18:19], v[18:19], v[130:131]
	v_pk_mul_f32 v[16:17], v[16:17], v[128:129]
	v_pk_mul_f32 v[92:93], v[92:93], v[2:3]
	v_pk_mul_f32 v[88:89], v[88:89], v[6:7]
	v_pk_mul_f32 v[84:85], v[84:85], v[10:11]
	v_pk_mul_f32 v[94:95], v[94:95], v[4:5]
	v_pk_mul_f32 v[90:91], v[90:91], v[8:9]
	v_pk_mul_f32 v[86:87], v[86:87], v[12:13]
	v_pk_mul_f32 v[82:83], v[82:83], v[130:131]
	v_pk_mul_f32 v[80:81], v[80:81], v[128:129]
.LgB_373:
	s_add_i32 s45, s45, 2
	s_add_u32 s100, s100, 0x4000
	s_addc_u32 s101, s101, 0
	s_add_u32 s98, s98, 0x8000
	s_addc_u32 s99, s99, 0
	s_cmpk_gt_u32 s45, 0x7d
	s_cbranch_scc1 .LBB0_385
	s_branch .LgBc2_374

.LgB_375:
	s_waitcnt vmcnt(2) lgkmcnt(0)
	s_barrier
	s_waitcnt lgkmcnt(0)
	v_mfma_scale_f32_32x32x64_f8f6f4 v[64:79], v[2:9], v[194:201], v[64:79], v240, v240 op_sel_hi:[0,0,0]
	v_exp_f32_e32 v144, v160
	v_exp_f32_e32 v145, v161
	v_exp_f32_e32 v146, v162
	v_mfma_scale_f32_32x32x64_f8f6f4 v[48:63], v[2:9], v[148:155], v[48:63], v240, v240 op_sel_hi:[0,0,0]
	v_exp_f32_e32 v147, v163
	v_exp_f32_e32 v148, v164
	v_exp_f32_e32 v149, v165
	v_mfma_scale_f32_32x32x64_f8f6f4 v[32:47], v[2:9], v[120:127], v[32:47], v240, v240 op_sel_hi:[0,0,0]
	v_exp_f32_e32 v150, v166
	v_exp_f32_e32 v151, v167
	v_exp_f32_e32 v152, v168
	v_mfma_scale_f32_32x32x64_f8f6f4 v[16:31], v[2:9], v[112:119], v[16:31], v240, v240 op_sel_hi:[0,0,0]
	v_exp_f32_e32 v153, v169
	v_exp_f32_e32 v154, v170
	v_exp_f32_e32 v155, v171
	v_mfma_scale_f32_32x32x64_f8f6f4 v[80:95], v[2:9], v[228:235], v[80:95], v240, v240 op_sel_hi:[0,0,0]
	v_exp_f32_e32 v156, v172
	v_exp_f32_e32 v157, v173
	v_exp_f32_e32 v158, v174
	v_exp_f32_e32 v159, v175
	s_waitcnt vmcnt(2)
	s_cmp_eq_u32 s93, 0
	s_cbranch_scc1 .LgB_379
	s_mov_b32 s93, 0
	s_and_saveexec_b64 s[56:57], s[4:5]
	ds_write_b32 v236, v1 offset:128
	s_or_b64 exec, exec, s[56:57]
	s_waitcnt lgkmcnt(0)
	v_add_u32_e32 v1, s67, v237
	ds_read_b128 v[2:5], v1 offset:224
	ds_read_b128 v[6:9], v1 offset:192
	ds_read_b128 v[10:13], v1 offset:160
	ds_read_b128 v[112:115], v1 offset:128
	s_waitcnt lgkmcnt(0)
	v_pk_mul_f32 v[76:77], v[76:77], v[2:3]
	v_pk_mul_f32 v[72:73], v[72:73], v[6:7]
	v_pk_mul_f32 v[68:69], v[68:69], v[10:11]
	v_pk_mul_f32 v[78:79], v[78:79], v[4:5]
	v_pk_mul_f32 v[74:75], v[74:75], v[8:9]
	v_pk_mul_f32 v[70:71], v[70:71], v[12:13]
	v_pk_mul_f32 v[66:67], v[66:67], v[114:115]
	v_pk_mul_f32 v[64:65], v[64:65], v[112:113]
	v_pk_mul_f32 v[60:61], v[60:61], v[2:3]
	v_pk_mul_f32 v[56:57], v[56:57], v[6:7]
	v_pk_mul_f32 v[52:53], v[52:53], v[10:11]
	v_pk_mul_f32 v[62:63], v[62:63], v[4:5]
	v_pk_mul_f32 v[58:59], v[58:59], v[8:9]
	v_pk_mul_f32 v[54:55], v[54:55], v[12:13]
	v_pk_mul_f32 v[50:51], v[50:51], v[114:115]
	v_pk_mul_f32 v[48:49], v[48:49], v[112:113]
	v_pk_mul_f32 v[44:45], v[44:45], v[2:3]
	v_pk_mul_f32 v[40:41], v[40:41], v[6:7]
	v_pk_mul_f32 v[36:37], v[36:37], v[10:11]
	v_pk_mul_f32 v[46:47], v[46:47], v[4:5]
	v_pk_mul_f32 v[42:43], v[42:43], v[8:9]
	v_pk_mul_f32 v[38:39], v[38:39], v[12:13]
	v_pk_mul_f32 v[34:35], v[34:35], v[114:115]
	v_pk_mul_f32 v[32:33], v[32:33], v[112:113]
	v_pk_mul_f32 v[28:29], v[28:29], v[2:3]
	v_pk_mul_f32 v[24:25], v[24:25], v[6:7]
	v_pk_mul_f32 v[20:21], v[20:21], v[10:11]
	v_pk_mul_f32 v[30:31], v[30:31], v[4:5]
	v_pk_mul_f32 v[26:27], v[26:27], v[8:9]
	v_pk_mul_f32 v[22:23], v[22:23], v[12:13]
	v_pk_mul_f32 v[18:19], v[18:19], v[114:115]
	v_pk_mul_f32 v[16:17], v[16:17], v[112:113]
	v_pk_mul_f32 v[92:93], v[92:93], v[2:3]
	v_pk_mul_f32 v[88:89], v[88:89], v[6:7]
	v_pk_mul_f32 v[84:85], v[84:85], v[10:11]
	v_pk_mul_f32 v[94:95], v[94:95], v[4:5]
	v_pk_mul_f32 v[90:91], v[90:91], v[8:9]
	v_pk_mul_f32 v[86:87], v[86:87], v[12:13]
	v_pk_mul_f32 v[82:83], v[82:83], v[114:115]
	v_pk_mul_f32 v[80:81], v[80:81], v[112:113]

.LgB_380:
	s_waitcnt vmcnt(2) lgkmcnt(0)
	s_barrier
	s_waitcnt lgkmcnt(0)
	v_mfma_scale_f32_32x32x64_f8f6f4 v[64:79], v[2:9], v[194:201], v[64:79], v240, v240 op_sel_hi:[0,0,0]
	v_exp_f32_e32 v144, v160
	v_exp_f32_e32 v145, v161
	v_exp_f32_e32 v146, v162
	v_mfma_scale_f32_32x32x64_f8f6f4 v[48:63], v[2:9], v[148:155], v[48:63], v240, v240 op_sel_hi:[0,0,0]
	v_exp_f32_e32 v147, v163
	v_exp_f32_e32 v148, v164
	v_exp_f32_e32 v149, v165
	v_mfma_scale_f32_32x32x64_f8f6f4 v[32:47], v[2:9], v[136:143], v[32:47], v240, v240 op_sel_hi:[0,0,0]
	v_exp_f32_e32 v150, v166
	v_exp_f32_e32 v151, v167
	v_exp_f32_e32 v152, v168
	v_mfma_scale_f32_32x32x64_f8f6f4 v[16:31], v[2:9], v[128:135], v[16:31], v240, v240 op_sel_hi:[0,0,0]
	v_exp_f32_e32 v153, v169
	v_exp_f32_e32 v154, v170
	v_exp_f32_e32 v155, v171
	v_mfma_scale_f32_32x32x64_f8f6f4 v[80:95], v[2:9], v[228:235], v[80:95], v240, v240 op_sel_hi:[0,0,0]
	v_exp_f32_e32 v156, v172
	v_exp_f32_e32 v157, v173
	v_exp_f32_e32 v158, v174
	v_exp_f32_e32 v159, v175
	s_waitcnt vmcnt(2)
	s_cmp_eq_u32 s93, 0
	s_cbranch_scc1 .LgB_373
	s_mov_b32 s93, 0
	s_and_saveexec_b64 s[56:57], s[4:5]
	s_cbranch_execz .LgB_372
	ds_write_b32 v236, v1 offset:128
	s_branch .LgB_372

; #define BAR() do { asm volatile("s_waitcnt lgkmcnt(0)" ::: "memory"); __builtin_amdgcn_s_barrier(); asm volatile("" ::: "memory"); } while (0)
; #define WAITV(n) asm volatile("s_waitcnt vmcnt(" #n ")" ::: "memory")
; #define RESC(a) do { if (__any((a) < 1.f)) { if (hi == 0) al_l[r32] = (a); asm volatile("s_waitcnt lgkmcnt(0)" ::: "memory"); \
;     for (int r = 0; r < 16; ++r) { const float a_ = al_l[crow(r, hi)]; ls[r] *= a_; for (int d = 0; d < 4; ++d) o[d][r] *= a_; } } } while (0)
; __device__ __forceinline__ void body(const unsigned char* Q8b, const unsigned char* K8h, const unsigned char* VT8h, const bf16_t* Gb, bf16_t* Ob, int seq, char* lds, const int wid, ...
;     ...
;     WAITV(2);
;     RESC(alA); BAR();
;     s0 = (s0 + 2) & 3;
;   }
.LgBc2_372:
	s_or_b64 exec, exec, s[56:57]
	s_waitcnt lgkmcnt(0)
	v_add_u32_e32 v1, s67, v237
	ds_read_b128 v[2:5], v1 offset:224
	ds_read_b128 v[6:9], v1 offset:192
	ds_read_b128 v[10:13], v1 offset:160
	ds_read_b128 v[128:131], v1 offset:128
	s_waitcnt lgkmcnt(0)
	v_pk_mul_f32 v[76:77], v[76:77], v[2:3]
	v_pk_mul_f32 v[72:73], v[72:73], v[6:7]
	v_pk_mul_f32 v[68:69], v[68:69], v[10:11]
	v_pk_mul_f32 v[78:79], v[78:79], v[4:5]
	v_pk_mul_f32 v[74:75], v[74:75], v[8:9]
	v_pk_mul_f32 v[70:71], v[70:71], v[12:13]
	v_pk_mul_f32 v[66:67], v[66:67], v[130:131]
	v_pk_mul_f32 v[64:65], v[64:65], v[128:129]
	v_pk_mul_f32 v[60:61], v[60:61], v[2:3]
	v_pk_mul_f32 v[56:57], v[56:57], v[6:7]
	v_pk_mul_f32 v[52:53], v[52:53], v[10:11]
	v_pk_mul_f32 v[62:63], v[62:63], v[4:5]
	v_pk_mul_f32 v[58:59], v[58:59], v[8:9]
	v_pk_mul_f32 v[54:55], v[54:55], v[12:13]
	v_pk_mul_f32 v[50:51], v[50:51], v[130:131]
	v_pk_mul_f32 v[48:49], v[48:49], v[128:129]
	v_pk_mul_f32 v[44:45], v[44:45], v[2:3]
	v_pk_mul_f32 v[40:41], v[40:41], v[6:7]
	v_pk_mul_f32 v[36:37], v[36:37], v[10:11]
	v_pk_mul_f32 v[46:47], v[46:47], v[4:5]
	v_pk_mul_f32 v[42:43], v[42:43], v[8:9]
	v_pk_mul_f32 v[38:39], v[38:39], v[12:13]
	v_pk_mul_f32 v[34:35], v[34:35], v[130:131]
	v_pk_mul_f32 v[32:33], v[32:33], v[128:129]
	v_pk_mul_f32 v[28:29], v[28:29], v[2:3]
	v_pk_mul_f32 v[24:25], v[24:25], v[6:7]
	v_pk_mul_f32 v[20:21], v[20:21], v[10:11]
	v_pk_mul_f32 v[30:31], v[30:31], v[4:5]
	v_pk_mul_f32 v[26:27], v[26:27], v[8:9]
	v_pk_mul_f32 v[22:23], v[22:23], v[12:13]
	v_pk_mul_f32 v[18:19], v[18:19], v[130:131]
	v_pk_mul_f32 v[16:17], v[16:17], v[128:129]
	v_pk_mul_f32 v[92:93], v[92:93], v[2:3]
	v_pk_mul_f32 v[88:89], v[88:89], v[6:7]
	v_pk_mul_f32 v[84:85], v[84:85], v[10:11]
	v_pk_mul_f32 v[94:95], v[94:95], v[4:5]
	v_pk_mul_f32 v[90:91], v[90:91], v[8:9]
	v_pk_mul_f32 v[86:87], v[86:87], v[12:13]
	v_pk_mul_f32 v[82:83], v[82:83], v[130:131]
	v_pk_mul_f32 v[80:81], v[80:81], v[128:129]
.LgBc2_373:
	s_add_i32 s45, s45, 2
	s_add_u32 s100, s100, 0x4000
	s_addc_u32 s101, s101, 0
	s_add_u32 s98, s98, 0x8000
	s_addc_u32 s99, s99, 0
	s_cmpk_gt_u32 s45, 0x7d
	s_cbranch_scc1 .LBB0_385
	s_branch .LgB_374
